# baseline (speedup 1.0000x reference)
;     __device__ __forceinline__ void operator()(const f32x4 (&acc)[2][2][4][2], const Unit& u, int wr, int wc, int fr, int fq) const {
;         int r0 = u.pm * BM + wr * 64 + fr; asm volatile("" : "+v"(r0)); const int col0 = u.pn * BM + wc * 32 + 4 * fq;
;         float* out = P + (size_t)u.ks * 1024 * 1024;
; #pragma unroll
;         for (int bj = 0; bj < 2; ++bj)
; #pragma unroll
;             for (int n = 0; n < 2; ++n) { const int cc = col0 + bj * HALF + n * 16; const f32x4 gv = *(const f32x4*)(gate + cc);
.LBB0_321:
	v_lshl_or_b32 v134, s67, 8, v137
	v_ashrrev_i32_e32 v135, 31, v134
	v_lshlrev_b64 v[144:145], 2, v[134:135]
	v_lshl_add_u32 v148, s68, 8, v3
	v_lshl_add_u64 v[140:141], s[34:35], 0, v[144:145]
	global_load_dwordx4 v[140:143], v[140:141], off
	v_or_b32_e32 v152, 16, v134
	v_ashrrev_i32_e32 v153, 31, v152
	v_lshl_add_u64 v[152:153], v[152:153], 2, s[34:35]
	global_load_dwordx4 v[152:155], v[152:153], off
	v_or_b32_e32 v156, 0x80, v134
	v_ashrrev_i32_e32 v157, 31, v156
	v_lshl_add_u64 v[156:157], v[156:157], 2, s[34:35]
	global_load_dwordx4 v[156:159], v[156:157], off
	v_or_b32_e32 v160, 0x90, v134
	v_ashrrev_i32_e32 v161, 31, v160
	v_lshl_add_u64 v[160:161], v[160:161], 2, s[34:35]
	global_load_dwordx4 v[160:163], v[160:161], off
	s_ashr_i32 s91, s90, 31
	s_lshl_b64 s[42:43], s[90:91], 22
	s_add_u32 s42, s18, s42
	s_addc_u32 s43, s19, s43
	v_ashrrev_i32_e32 v149, 31, v148
	v_lshl_add_u64 v[150:151], s[42:43], 0, v[144:145]
	s_mov_b32 s9, 0x10000
	s_mov_b64 s[42:43], 0x20000
	v_mov_b32_e32 v238, v248
	v_mov_b32_e32 v248, v208
	v_mov_b64_e32 v[208:209], v[210:211]
	v_mov_b64_e32 v[210:211], 0x1ff
	s_waitcnt vmcnt(0) lgkmcnt(0)
;     __device__ __forceinline__ void operator()(const f32x4 (&acc)[2][2][4][2], const Unit& u, int wr, int wc, int fr, int fq) const {
;     ...
;             for (int n = 0; n < 2; ++n) { const int cc = col0 + bj * HALF + n * 16; const f32x4 gv = *(const f32x4*)(gate + cc);
; #pragma unroll
;                 for (int ai = 0; ai < 2; ++ai)
; #pragma unroll
;                     for (int m = 0; m < 4; ++m) *(f32x4*)(out + (size_t)(r0 + ai * HALF + m * 16) * 1024 + cc) = gv * acc[ai][bj][m][n]; }
	v_pk_mul_f32 v[144:145], v[112:113], v[140:141]
	v_lshlrev_b64 v[112:113], 12, v[148:149]
	v_pk_mul_f32 v[146:147], v[114:115], v[142:143]
	v_lshl_add_u64 v[114:115], v[150:151], 0, v[112:113]
	global_store_dwordx4 v[114:115], v[144:147], off
	v_pk_mul_f32 v[110:111], v[110:111], v[142:143]
	v_pk_mul_f32 v[108:109], v[108:109], v[140:141]
	v_add_co_u32_e32 v144, vcc, s9, v114
	s_mov_b32 s9, 0x20000
	s_nop 0
	v_addc_co_u32_e32 v145, vcc, 0, v115, vcc
	global_store_dwordx4 v[144:145], v[108:111], off
	v_pk_mul_f32 v[106:107], v[106:107], v[142:143]
	v_pk_mul_f32 v[104:105], v[104:105], v[140:141]
	v_add_co_u32_e32 v108, vcc, s9, v114
	s_mov_b32 s9, 0x30000
	s_nop 0
	v_addc_co_u32_e32 v109, vcc, 0, v115, vcc
	global_store_dwordx4 v[108:109], v[104:107], off
	v_pk_mul_f32 v[102:103], v[102:103], v[142:143]
	v_pk_mul_f32 v[100:101], v[100:101], v[140:141]
	v_add_co_u32_e32 v104, vcc, s9, v114
	s_mov_b32 s9, 0x80000
	s_nop 0
	v_addc_co_u32_e32 v105, vcc, 0, v115, vcc
	global_store_dwordx4 v[104:105], v[100:103], off
	v_add_co_u32_e32 v104, vcc, s9, v114
	s_nop 0
	v_pk_mul_f32 v[102:103], v[130:131], v[142:143]
	v_pk_mul_f32 v[100:101], v[128:129], v[140:141]
	v_addc_co_u32_e32 v105, vcc, 0, v115, vcc
	s_mov_b32 s9, 0x90000
	global_store_dwordx4 v[104:105], v[100:103], off
	v_pk_mul_f32 v[122:123], v[122:123], v[142:143]
	v_pk_mul_f32 v[120:121], v[120:121], v[140:141]
	v_pk_mul_f32 v[100:101], v[124:125], v[140:141]
	v_add_co_u32_e32 v124, vcc, s9, v114
	v_pk_mul_f32 v[102:103], v[126:127], v[142:143]
	s_nop 0
	v_addc_co_u32_e32 v125, vcc, 0, v115, vcc
	s_mov_b32 s9, 0xa0000
	global_store_dwordx4 v[124:125], v[100:103], off
	v_pk_mul_f32 v[118:119], v[118:119], v[142:143]
	v_pk_mul_f32 v[116:117], v[116:117], v[140:141]
	v_add_co_u32_e32 v100, vcc, s9, v114
	s_mov_b32 s9, 0xb0000
	s_nop 0
	v_addc_co_u32_e32 v101, vcc, 0, v115, vcc
	global_store_dwordx4 v[100:101], v[120:123], off
	v_lshl_add_u64 v[112:113], v[114:115], 0, s[60:61]
	v_lshl_add_u64 v[110:111], v[114:115], 0, s[42:43]
	v_add_co_u32_e32 v120, vcc, s9, v114
	s_mov_b64 s[42:43], 0x30000
	s_nop 0
	v_addc_co_u32_e32 v121, vcc, 0, v115, vcc
	global_store_dwordx4 v[120:121], v[116:119], off
	v_lshl_add_u64 v[108:109], v[114:115], 0, s[42:43]
	s_mov_b64 s[42:43], 0x80000
	v_lshl_add_u64 v[106:107], v[114:115], 0, s[42:43]
	s_mov_b64 s[42:43], 0x90000
	v_lshl_add_u64 v[104:105], v[114:115], 0, s[42:43]
	s_mov_b64 s[42:43], 0xa0000
	v_lshl_add_u64 v[102:103], v[114:115], 0, s[42:43]
	s_mov_b64 s[42:43], 0xb0000
	v_lshl_add_u64 v[100:101], v[114:115], 0, s[42:43]
	s_mov_b64 s[42:43], -1
	s_and_b64 vcc, exec, s[4:5]
	v_pk_mul_f32 v[70:71], v[70:71], v[154:155]
	v_pk_mul_f32 v[68:69], v[68:69], v[152:153]
	global_store_dwordx4 v[114:115], v[68:71], off offset:64
	s_nop 1
	v_pk_mul_f32 v[70:71], v[74:75], v[154:155]
	v_pk_mul_f32 v[68:69], v[72:73], v[152:153]
	global_store_dwordx4 v[112:113], v[68:71], off offset:64
	s_nop 1
	v_pk_mul_f32 v[70:71], v[78:79], v[154:155]
	v_pk_mul_f32 v[68:69], v[76:77], v[152:153]
	global_store_dwordx4 v[110:111], v[68:71], off offset:64
	s_nop 1
	v_pk_mul_f32 v[70:71], v[82:83], v[154:155]
	v_pk_mul_f32 v[68:69], v[80:81], v[152:153]
	global_store_dwordx4 v[108:109], v[68:71], off offset:64
	s_nop 1
	v_pk_mul_f32 v[70:71], v[86:87], v[154:155]
	v_pk_mul_f32 v[68:69], v[84:85], v[152:153]
	global_store_dwordx4 v[106:107], v[68:71], off offset:64
	s_nop 1
	v_pk_mul_f32 v[70:71], v[90:91], v[154:155]
	v_pk_mul_f32 v[68:69], v[88:89], v[152:153]
	global_store_dwordx4 v[104:105], v[68:71], off offset:64
	s_nop 1
	v_pk_mul_f32 v[70:71], v[94:95], v[154:155]
	v_pk_mul_f32 v[68:69], v[92:93], v[152:153]
	global_store_dwordx4 v[102:103], v[68:71], off offset:64
	s_nop 1
	v_pk_mul_f32 v[70:71], v[98:99], v[154:155]
	v_pk_mul_f32 v[68:69], v[96:97], v[152:153]
	global_store_dwordx4 v[100:101], v[68:71], off offset:64
	s_nop 1
	v_pk_mul_f32 v[38:39], v[38:39], v[158:159]
	v_pk_mul_f32 v[36:37], v[36:37], v[156:157]
	global_store_dwordx4 v[114:115], v[36:39], off offset:512
	s_nop 1
	v_pk_mul_f32 v[38:39], v[42:43], v[158:159]
	v_pk_mul_f32 v[36:37], v[40:41], v[156:157]
	global_store_dwordx4 v[112:113], v[36:39], off offset:512
	s_nop 1
	v_pk_mul_f32 v[38:39], v[46:47], v[158:159]
	v_pk_mul_f32 v[36:37], v[44:45], v[156:157]
	global_store_dwordx4 v[110:111], v[36:39], off offset:512
	s_nop 1
	v_pk_mul_f32 v[38:39], v[50:51], v[158:159]
	v_pk_mul_f32 v[36:37], v[48:49], v[156:157]
	global_store_dwordx4 v[108:109], v[36:39], off offset:512
	s_nop 1
	v_pk_mul_f32 v[38:39], v[54:55], v[158:159]
	v_pk_mul_f32 v[36:37], v[52:53], v[156:157]
	global_store_dwordx4 v[106:107], v[36:39], off offset:512
	s_nop 1
	v_pk_mul_f32 v[38:39], v[58:59], v[158:159]
	v_pk_mul_f32 v[36:37], v[56:57], v[156:157]
	global_store_dwordx4 v[104:105], v[36:39], off offset:512
	s_nop 1
	v_pk_mul_f32 v[38:39], v[62:63], v[158:159]
	v_pk_mul_f32 v[36:37], v[60:61], v[156:157]
	global_store_dwordx4 v[102:103], v[36:39], off offset:512
	s_nop 1
	v_pk_mul_f32 v[38:39], v[66:67], v[158:159]
	v_pk_mul_f32 v[36:37], v[64:65], v[156:157]
	global_store_dwordx4 v[100:101], v[36:39], off offset:512
	s_nop 1
	v_pk_mul_f32 v[6:7], v[6:7], v[162:163]
	v_pk_mul_f32 v[4:5], v[4:5], v[160:161]
	global_store_dwordx4 v[108:109], v[4:7], off offset:576
	v_pk_mul_f32 v[18:19], v[18:19], v[162:163]
	v_pk_mul_f32 v[16:17], v[16:17], v[160:161]
	v_pk_mul_f32 v[6:7], v[34:35], v[162:163]
	v_pk_mul_f32 v[4:5], v[32:33], v[160:161]
	global_store_dwordx4 v[106:107], v[4:7], off offset:576
	v_pk_mul_f32 v[14:15], v[14:15], v[162:163]
	v_pk_mul_f32 v[12:13], v[12:13], v[160:161]
	v_pk_mul_f32 v[6:7], v[30:31], v[162:163]
	v_pk_mul_f32 v[4:5], v[28:29], v[160:161]
	global_store_dwordx4 v[104:105], v[4:7], off offset:576
	v_pk_mul_f32 v[10:11], v[10:11], v[162:163]
	v_pk_mul_f32 v[8:9], v[8:9], v[160:161]
	v_pk_mul_f32 v[6:7], v[26:27], v[162:163]
	v_pk_mul_f32 v[4:5], v[24:25], v[160:161]
	global_store_dwordx4 v[102:103], v[4:7], off offset:576
	global_store_dwordx4 v[114:115], v[16:19], off offset:576
	global_store_dwordx4 v[112:113], v[12:15], off offset:576
	v_pk_mul_f32 v[6:7], v[22:23], v[162:163]
	v_pk_mul_f32 v[4:5], v[20:21], v[160:161]
	global_store_dwordx4 v[110:111], v[8:11], off offset:576
	global_store_dwordx4 v[100:101], v[4:7], off offset:576
	s_cbranch_vccnz .LBB0_312
	s_andn2_b64 vcc, exec, s[6:7]
	s_cbranch_vccnz .LBB0_311
	s_barrier
	s_branch .LBB0_311

;     __device__ __forceinline__ void operator()(const f32x4 (&acc)[2][2][4][2], const Unit& u, int wr, int wc, int fr, int fq) const {
;         int r0 = u.pm * BM + wr * 64 + fr; asm volatile("" : "+v"(r0)); const int col0 = u.pn * BM + wc * 32 + 4 * fq;
;         float* out = P + (size_t)u.ks * 1024 * 1024;
; #pragma unroll
;         for (int bj = 0; bj < 2; ++bj)
; #pragma unroll
;             for (int n = 0; n < 2; ++n) { const int cc = col0 + bj * HALF + n * 16; const f32x4 gv = *(const f32x4*)(gate + cc);
.LBB0_450:
	v_lshl_or_b32 v134, s94, 8, v137
	v_ashrrev_i32_e32 v135, 31, v134
	v_lshlrev_b64 v[144:145], 2, v[134:135]
	v_lshl_add_u32 v148, s96, 8, v3
	v_lshl_add_u64 v[140:141], s[30:31], 0, v[144:145]
	global_load_dwordx4 v[140:143], v[140:141], off
	v_or_b32_e32 v152, 16, v134
	v_ashrrev_i32_e32 v153, 31, v152
	v_lshl_add_u64 v[152:153], v[152:153], 2, s[30:31]
	global_load_dwordx4 v[152:155], v[152:153], off
	v_or_b32_e32 v156, 0x80, v134
	v_ashrrev_i32_e32 v157, 31, v156
	v_lshl_add_u64 v[156:157], v[156:157], 2, s[30:31]
	global_load_dwordx4 v[156:159], v[156:157], off
	v_or_b32_e32 v160, 0x90, v134
	v_ashrrev_i32_e32 v161, 31, v160
	v_lshl_add_u64 v[160:161], v[160:161], 2, s[30:31]
	global_load_dwordx4 v[160:163], v[160:161], off
	s_ashr_i32 s93, s92, 31
	s_lshl_b64 s[64:65], s[92:93], 22
	s_add_u32 s64, s16, s64
	s_addc_u32 s65, s17, s65
	v_ashrrev_i32_e32 v149, 31, v148
	v_lshl_add_u64 v[150:151], s[64:65], 0, v[144:145]
	s_mov_b32 s9, 0x10000
	s_mov_b64 s[58:59], 0x20000
	s_mov_b64 s[88:89], -1
	v_mov_b32_e32 v238, v248
	v_mov_b32_e32 v248, v208
	v_mov_b64_e32 v[208:209], v[210:211]
	v_mov_b64_e32 v[210:211], 0x1ff
	s_waitcnt vmcnt(0) lgkmcnt(0)
;     __device__ __forceinline__ void operator()(const f32x4 (&acc)[2][2][4][2], const Unit& u, int wr, int wc, int fr, int fq) const {
;     ...
;             for (int n = 0; n < 2; ++n) { const int cc = col0 + bj * HALF + n * 16; const f32x4 gv = *(const f32x4*)(gate + cc);
; #pragma unroll
;                 for (int ai = 0; ai < 2; ++ai)
; #pragma unroll
;                     for (int m = 0; m < 4; ++m) *(f32x4*)(out + (size_t)(r0 + ai * HALF + m * 16) * 1024 + cc) = gv * acc[ai][bj][m][n]; }
	v_pk_mul_f32 v[144:145], v[112:113], v[140:141]
	v_lshlrev_b64 v[112:113], 12, v[148:149]
	v_pk_mul_f32 v[146:147], v[114:115], v[142:143]
	v_lshl_add_u64 v[114:115], v[150:151], 0, v[112:113]
	global_store_dwordx4 v[114:115], v[144:147], off
	v_pk_mul_f32 v[110:111], v[110:111], v[142:143]
	v_pk_mul_f32 v[108:109], v[108:109], v[140:141]
	v_add_co_u32_e32 v144, vcc, s9, v114
	s_mov_b32 s9, 0x20000
	s_nop 0
	v_addc_co_u32_e32 v145, vcc, 0, v115, vcc
	global_store_dwordx4 v[144:145], v[108:111], off
	v_pk_mul_f32 v[106:107], v[106:107], v[142:143]
	v_pk_mul_f32 v[104:105], v[104:105], v[140:141]
	v_add_co_u32_e32 v108, vcc, s9, v114
	s_mov_b32 s9, 0x30000
	s_nop 0
	v_addc_co_u32_e32 v109, vcc, 0, v115, vcc
	global_store_dwordx4 v[108:109], v[104:107], off
	v_pk_mul_f32 v[102:103], v[102:103], v[142:143]
	v_pk_mul_f32 v[100:101], v[100:101], v[140:141]
	v_add_co_u32_e32 v104, vcc, s9, v114
	s_mov_b32 s9, 0x80000
	s_nop 0
	v_addc_co_u32_e32 v105, vcc, 0, v115, vcc
	global_store_dwordx4 v[104:105], v[100:103], off
	v_add_co_u32_e32 v104, vcc, s9, v114
	s_nop 0
	v_pk_mul_f32 v[102:103], v[130:131], v[142:143]
	v_pk_mul_f32 v[100:101], v[128:129], v[140:141]
	v_addc_co_u32_e32 v105, vcc, 0, v115, vcc
	s_mov_b32 s9, 0x90000
	global_store_dwordx4 v[104:105], v[100:103], off
	v_pk_mul_f32 v[122:123], v[122:123], v[142:143]
	v_pk_mul_f32 v[120:121], v[120:121], v[140:141]
	v_pk_mul_f32 v[100:101], v[124:125], v[140:141]
	v_add_co_u32_e32 v124, vcc, s9, v114
	v_pk_mul_f32 v[102:103], v[126:127], v[142:143]
	s_nop 0
	v_addc_co_u32_e32 v125, vcc, 0, v115, vcc
	s_mov_b32 s9, 0xa0000
	global_store_dwordx4 v[124:125], v[100:103], off
	v_pk_mul_f32 v[118:119], v[118:119], v[142:143]
	v_pk_mul_f32 v[116:117], v[116:117], v[140:141]
	v_add_co_u32_e32 v100, vcc, s9, v114
	s_mov_b32 s9, 0xb0000
	s_nop 0
	v_addc_co_u32_e32 v101, vcc, 0, v115, vcc
	global_store_dwordx4 v[100:101], v[120:123], off
	v_lshl_add_u64 v[112:113], v[114:115], 0, s[60:61]
	v_lshl_add_u64 v[110:111], v[114:115], 0, s[58:59]
	v_add_co_u32_e32 v120, vcc, s9, v114
	s_mov_b64 s[58:59], 0x30000
	s_nop 0
	v_addc_co_u32_e32 v121, vcc, 0, v115, vcc
	global_store_dwordx4 v[120:121], v[116:119], off
	v_lshl_add_u64 v[108:109], v[114:115], 0, s[58:59]
	s_mov_b64 s[58:59], 0x80000
	v_lshl_add_u64 v[106:107], v[114:115], 0, s[58:59]
	s_mov_b64 s[58:59], 0x90000
	v_lshl_add_u64 v[104:105], v[114:115], 0, s[58:59]
	s_mov_b64 s[58:59], 0xa0000
	v_lshl_add_u64 v[102:103], v[114:115], 0, s[58:59]
	s_mov_b64 s[58:59], 0xb0000
	v_lshl_add_u64 v[100:101], v[114:115], 0, s[58:59]
	s_and_b64 vcc, exec, s[4:5]
	s_mov_b32 s58, 0xf800000
	s_mov_b32 s59, 0x615c000
	v_pk_mul_f32 v[70:71], v[70:71], v[154:155]
	v_pk_mul_f32 v[68:69], v[68:69], v[152:153]
	global_store_dwordx4 v[114:115], v[68:71], off offset:64
	s_nop 1
	v_pk_mul_f32 v[70:71], v[74:75], v[154:155]
	v_pk_mul_f32 v[68:69], v[72:73], v[152:153]
	global_store_dwordx4 v[112:113], v[68:71], off offset:64
	s_nop 1
	v_pk_mul_f32 v[70:71], v[78:79], v[154:155]
	v_pk_mul_f32 v[68:69], v[76:77], v[152:153]
	global_store_dwordx4 v[110:111], v[68:71], off offset:64
	s_nop 1
	v_pk_mul_f32 v[70:71], v[82:83], v[154:155]
	v_pk_mul_f32 v[68:69], v[80:81], v[152:153]
	global_store_dwordx4 v[108:109], v[68:71], off offset:64
	s_nop 1
	v_pk_mul_f32 v[70:71], v[86:87], v[154:155]
	v_pk_mul_f32 v[68:69], v[84:85], v[152:153]
	global_store_dwordx4 v[106:107], v[68:71], off offset:64
	s_nop 1
	v_pk_mul_f32 v[70:71], v[90:91], v[154:155]
	v_pk_mul_f32 v[68:69], v[88:89], v[152:153]
	global_store_dwordx4 v[104:105], v[68:71], off offset:64
	s_nop 1
	v_pk_mul_f32 v[70:71], v[94:95], v[154:155]
	v_pk_mul_f32 v[68:69], v[92:93], v[152:153]
	global_store_dwordx4 v[102:103], v[68:71], off offset:64
	s_nop 1
	v_pk_mul_f32 v[70:71], v[98:99], v[154:155]
	v_pk_mul_f32 v[68:69], v[96:97], v[152:153]
	global_store_dwordx4 v[100:101], v[68:71], off offset:64
	s_nop 1
	v_pk_mul_f32 v[38:39], v[38:39], v[158:159]
	v_pk_mul_f32 v[36:37], v[36:37], v[156:157]
	global_store_dwordx4 v[114:115], v[36:39], off offset:512
	s_nop 1
	v_pk_mul_f32 v[38:39], v[42:43], v[158:159]
	v_pk_mul_f32 v[36:37], v[40:41], v[156:157]
	global_store_dwordx4 v[112:113], v[36:39], off offset:512
	s_nop 1
	v_pk_mul_f32 v[38:39], v[46:47], v[158:159]
	v_pk_mul_f32 v[36:37], v[44:45], v[156:157]
	global_store_dwordx4 v[110:111], v[36:39], off offset:512
	s_nop 1
	v_pk_mul_f32 v[38:39], v[50:51], v[158:159]
	v_pk_mul_f32 v[36:37], v[48:49], v[156:157]
	global_store_dwordx4 v[108:109], v[36:39], off offset:512
	s_nop 1
	v_pk_mul_f32 v[38:39], v[54:55], v[158:159]
	v_pk_mul_f32 v[36:37], v[52:53], v[156:157]
	global_store_dwordx4 v[106:107], v[36:39], off offset:512
	s_nop 1
	v_pk_mul_f32 v[38:39], v[58:59], v[158:159]
	v_pk_mul_f32 v[36:37], v[56:57], v[156:157]
	global_store_dwordx4 v[104:105], v[36:39], off offset:512
	s_nop 1
	v_pk_mul_f32 v[38:39], v[62:63], v[158:159]
	v_pk_mul_f32 v[36:37], v[60:61], v[156:157]
	global_store_dwordx4 v[102:103], v[36:39], off offset:512
	s_nop 1
	v_pk_mul_f32 v[38:39], v[66:67], v[158:159]
	v_pk_mul_f32 v[36:37], v[64:65], v[156:157]
	global_store_dwordx4 v[100:101], v[36:39], off offset:512
	s_nop 1
	v_pk_mul_f32 v[6:7], v[6:7], v[162:163]
	v_pk_mul_f32 v[4:5], v[4:5], v[160:161]
	global_store_dwordx4 v[108:109], v[4:7], off offset:576
	v_pk_mul_f32 v[18:19], v[18:19], v[162:163]
	v_pk_mul_f32 v[16:17], v[16:17], v[160:161]
	v_pk_mul_f32 v[6:7], v[34:35], v[162:163]
	v_pk_mul_f32 v[4:5], v[32:33], v[160:161]
	global_store_dwordx4 v[106:107], v[4:7], off offset:576
	v_pk_mul_f32 v[14:15], v[14:15], v[162:163]
	v_pk_mul_f32 v[12:13], v[12:13], v[160:161]
	v_pk_mul_f32 v[6:7], v[30:31], v[162:163]
	v_pk_mul_f32 v[4:5], v[28:29], v[160:161]
	global_store_dwordx4 v[104:105], v[4:7], off offset:576
	v_pk_mul_f32 v[10:11], v[10:11], v[162:163]
	v_pk_mul_f32 v[8:9], v[8:9], v[160:161]
	v_pk_mul_f32 v[6:7], v[26:27], v[162:163]
	v_pk_mul_f32 v[4:5], v[24:25], v[160:161]
	global_store_dwordx4 v[102:103], v[4:7], off offset:576
	global_store_dwordx4 v[114:115], v[16:19], off offset:576
	global_store_dwordx4 v[112:113], v[12:15], off offset:576
	v_pk_mul_f32 v[6:7], v[22:23], v[162:163]
	v_pk_mul_f32 v[4:5], v[20:21], v[160:161]
	global_store_dwordx4 v[110:111], v[8:11], off offset:576
	global_store_dwordx4 v[100:101], v[4:7], off offset:576
	s_cbranch_vccnz .LBB0_441
	s_andn2_b64 vcc, exec, s[6:7]
	s_cbranch_vccnz .LBB0_440
	s_barrier
	s_branch .LBB0_440

; #define LAS __attribute__((address_space(3)))
; __device__ __forceinline__ void attn_blk(bool ctx_too, const bf16_t* U, bf16_t* Y, const float* nb_l, LAS unsigned char* lds, int lane, int wave, int tid) {
;     LAS float* sb = (LAS float*)lds;
;     for (int i = tid; i < NH * 15 * 31; i += NTHR) sb[64 + i] = nb_l[i] * LOG2E;
;     if (tid < 64) { sb[tid] = 0.f; sb[64 + NH * 15 * 31 + tid] = 0.f; }
.LBB0_455:
	s_and_b64 vcc, exec, s[4:5]
	s_cbranch_vccz .LBB0_533
	s_movk_i32 s0, 0xe88
	v_cmp_gt_i32_e32 vcc, s0, v212
	s_and_saveexec_b64 s[4:5], vcc
	s_cbranch_execz .LBB0_459
	s_load_dwordx2 s[0:1], s[28:29], 0x58
	s_lshr_b64 s[6:7], s[48:49], 3
	s_lshr_b32 s3, s49, 3
	s_mulk_i32 s3, 0x3a20
	s_mul_hi_u32 s7, s6, 0x3a20
	s_add_i32 s7, s7, s3
	s_mul_i32 s3, s6, 0x3a20
	s_add_i32 s6, 0, 0x100
	s_waitcnt lgkmcnt(0)
	s_add_u32 s0, s0, s3
	v_ashrrev_i32_e32 v213, 31, v212
	s_addc_u32 s1, s1, s7
	v_add_u32_e32 v3, 0xfffffe00, v212
	v_lshl_add_u32 v4, v212, 2, s6
	v_lshl_add_u64 v[0:1], v[212:213], 2, s[0:1]
	s_mov_b64 s[0:1], 0x1000
	global_load_dword v5, v[0:1], off
	global_load_dword v6, v[0:1], off offset:2048
	v_lshl_add_u64 v[0:1], v[0:1], 0, s[0:1]
	global_load_dword v7, v[0:1], off
	global_load_dword v8, v[0:1], off offset:2048
	v_lshl_add_u64 v[0:1], v[0:1], 0, s[0:1]
	global_load_dword v9, v[0:1], off
	global_load_dword v10, v[0:1], off offset:2048
	v_lshl_add_u64 v[0:1], v[0:1], 0, s[0:1]
	global_load_dword v11, v[0:1], off
	s_movk_i32 s0, 0x88
	v_cmp_gt_i32_e32 vcc, s0, v212
	s_and_saveexec_b64 s[6:7], vcc
	global_load_dword v12, v[0:1], off offset:2048
	s_mov_b64 exec, s[6:7]
	s_waitcnt vmcnt(0)
	v_mul_f32_e32 v5, 0x3fb8aa3b, v5
	v_mul_f32_e32 v6, 0x3fb8aa3b, v6
	v_mul_f32_e32 v7, 0x3fb8aa3b, v7
	v_mul_f32_e32 v8, 0x3fb8aa3b, v8
	v_mul_f32_e32 v9, 0x3fb8aa3b, v9
	v_mul_f32_e32 v10, 0x3fb8aa3b, v10
	v_mul_f32_e32 v11, 0x3fb8aa3b, v11
	ds_write_b32 v4, v5
	ds_write_b32 v4, v6 offset:2048
	ds_write_b32 v4, v7 offset:4096
	ds_write_b32 v4, v8 offset:6144
	ds_write_b32 v4, v9 offset:8192
	ds_write_b32 v4, v10 offset:10240
	ds_write_b32 v4, v11 offset:12288
	s_and_saveexec_b64 s[6:7], vcc
	v_mul_f32_e32 v12, 0x3fb8aa3b, v12
	ds_write_b32 v4, v12 offset:14336
	s_mov_b64 exec, s[6:7]
